# P5 loop: weight/bias rows loaded once before the loop instead of per item (on top of two items per trip)
# speedup vs baseline: 1.0023x; 1.0023x over previous
.LBB0_1611:
	v_lshrrev_b32_e32 v2, 6, v1
	v_readlane_b32 s2, v245, 0
	v_readlane_b32 s3, v245, 1
	s_nop 0
	v_lshl_add_u32 v3, s2, 2, v2
	s_mov_b32 s2, 0x8500
	v_cmp_gt_i32_e32 vcc, s2, v3
	s_and_saveexec_b64 s[2:3], vcc
	s_cbranch_execz .LBB0_1614
	v_and_b32_e32 v2, 63, v1
	v_bfe_u32 v4, v1, 6, 1
	s_add_u32 s4, s82, 0xa380000
	v_lshlrev_b32_e32 v2, 3, v2
	v_mov_b32_e32 v9, 0
	v_lshlrev_b32_e32 v8, 5, v4
	v_lshrrev_b32_e32 v1, 1, v1
	s_addc_u32 s5, s83, 0
	v_lshl_or_b32 v2, v4, 9, v2
	v_lshl_add_u64 v[4:5], s[82:83], 0, v[8:9]
	v_and_b32_e32 v8, 28, v1
	v_readlane_b32 s16, v245, 44
	s_add_u32 s6, s82, 0x10740000
	v_lshl_add_u64 v[4:5], v[4:5], 0, v[8:9]
	v_lshlrev_b32_e32 v8, 2, v2
	v_readlane_b32 s17, v245, 45
	v_readlane_b32 s18, v245, 46
	v_readlane_b32 s19, v245, 47
	v_readlane_b32 s20, v245, 48
	v_readlane_b32 s21, v245, 49
	v_readlane_b32 s22, v245, 50
	v_readlane_b32 s23, v245, 51
	v_readlane_b32 s24, v245, 52
	v_readlane_b32 s25, v245, 53
	v_readlane_b32 s26, v245, 54
	v_readlane_b32 s27, v245, 55
	v_readlane_b32 s28, v245, 56
	v_readlane_b32 s29, v245, 57
	v_readlane_b32 s30, v245, 58
	v_readlane_b32 s31, v245, 59
	s_addc_u32 s7, s83, 0
	v_readlane_b32 s12, v245, 7
	v_lshl_add_u64 v[6:7], s[30:31], 0, v[8:9]
	v_readlane_b32 s16, v245, 60
	s_add_u32 s8, s82, 0x18c40000
	v_readlane_b32 s13, v245, 8
	v_readlane_b32 s14, v245, 9
	s_mov_b64 s[10:11], 0x1b9fc000
	v_readlane_b32 s17, v245, 61
	s_addc_u32 s9, s83, 0
	s_lshl_b32 s12, s14, 2
	v_lshl_add_u64 v[4:5], v[4:5], 0, s[10:11]
	v_lshl_add_u64 v[8:9], s[16:17], 0, v[8:9]
	s_mov_b64 s[10:11], 0
	v_mov_b32_e32 v1, 0x3a27c5ac
	s_mov_b32 s13, 0x800000
	s_mov_b32 s14, 0x84ff
	v_readlane_b32 s15, v245, 10
	v_readlane_b32 s18, v245, 62
	v_readlane_b32 s19, v245, 63
	v_readlane_b32 s20, v244, 0
	v_readlane_b32 s21, v244, 1
	v_readlane_b32 s22, v244, 2
	v_readlane_b32 s23, v244, 3
	v_readlane_b32 s24, v244, 4
	v_readlane_b32 s25, v244, 5
	v_readlane_b32 s26, v244, 6
	v_readlane_b32 s27, v244, 7
	v_readlane_b32 s28, v244, 8
	v_readlane_b32 s29, v244, 9
	v_readlane_b32 s30, v244, 10
	v_readlane_b32 s31, v244, 11
	global_load_dwordx4 v[236:239], v[6:7], off offset:16
	global_load_dwordx4 v[232:235], v[6:7], off
	global_load_dwordx4 v[246:249], v[8:9], off offset:16
	global_load_dwordx4 v[240:243], v[8:9], off
.LBB0_1613:
	v_readfirstlane_b32 s84, v3
	s_nop 0
	s_add_i32 s84, s84, s12
	s_cmp_gt_i32 s84, s14
	s_cbranch_scc1 .Lp5_single
	s_waitcnt vmcnt(6)
	v_ashrrev_i32_e32 v26, 1, v3
	v_ashrrev_i32_e32 v27, 31, v26
	v_lshlrev_b64 v[28:29], 11, v[26:27]
	v_lshlrev_b64 v[26:27], 6, v[26:27]
	v_lshl_or_b32 v28, v2, 1, v28
	s_waitcnt vmcnt(4)
	v_lshl_add_u64 v[38:39], v[4:5], 0, v[26:27]
	v_lshl_add_u64 v[40:41], s[4:5], 0, v[28:29]
	v_lshl_add_u64 v[30:31], s[6:7], 0, v[28:29]
	v_lshl_add_u64 v[34:35], s[8:9], 0, v[28:29]
	global_load_dwordx4 v[26:29], v[40:41], off
	s_nop 0
	global_load_dwordx4 v[30:33], v[30:31], off
	s_nop 0
	global_load_dwordx4 v[34:37], v[34:35], off
	s_nop 0
	global_load_dword v38, v[38:39], off
	v_add_u32_e32 v126, s12, v3
	v_ashrrev_i32_e32 v90, 1, v126
	v_ashrrev_i32_e32 v91, 31, v90
	v_lshlrev_b64 v[92:93], 11, v[90:91]
	v_lshlrev_b64 v[90:91], 6, v[90:91]
	v_lshl_or_b32 v92, v2, 1, v92
	v_lshl_add_u64 v[102:103], v[4:5], 0, v[90:91]
	v_lshl_add_u64 v[104:105], s[4:5], 0, v[92:93]
	v_lshl_add_u64 v[94:95], s[6:7], 0, v[92:93]
	v_lshl_add_u64 v[98:99], s[8:9], 0, v[92:93]
	global_load_dwordx4 v[90:93], v[104:105], off
	s_nop 0
	global_load_dwordx4 v[94:97], v[94:95], off
	s_nop 0
	global_load_dwordx4 v[98:101], v[98:99], off
	s_nop 0
	global_load_dword v102, v[102:103], off
	v_add_u32_e32 v3, s12, v126
	v_cmp_lt_i32_e32 vcc, s14, v3
	s_or_b64 s[10:11], vcc, s[10:11]
	s_waitcnt vmcnt(7)
	v_lshlrev_b32_e32 v42, 16, v26
	v_and_b32_e32 v43, 0xffff0000, v26
	v_add_f32_e32 v39, 0, v42
	v_lshlrev_b32_e32 v26, 16, v27
	v_add_f32_e32 v39, v39, v43
	v_and_b32_e32 v27, 0xffff0000, v27
	v_add_f32_e32 v39, v39, v26
	v_lshlrev_b32_e32 v44, 16, v28
	v_add_f32_e32 v39, v39, v27
	v_and_b32_e32 v45, 0xffff0000, v28
	v_add_f32_e32 v39, v39, v44
	v_lshlrev_b32_e32 v28, 16, v29
	v_add_f32_e32 v39, v39, v45
	v_and_b32_e32 v29, 0xffff0000, v29
	v_add_f32_e32 v39, v39, v28
	v_add_f32_e32 v39, v39, v29
	s_waitcnt vmcnt(6)
	v_lshlrev_b32_e32 v46, 16, v30
	v_and_b32_e32 v47, 0xffff0000, v30
	v_add_f32_dpp v39, v39, v39 quad_perm:[1,0,3,2] row_mask:0xf bank_mask:0xf bound_ctrl:1
	v_lshlrev_b32_e32 v30, 16, v31
	v_and_b32_e32 v31, 0xffff0000, v31
	v_add_f32_dpp v39, v39, v39 quad_perm:[2,3,0,1] row_mask:0xf bank_mask:0xf bound_ctrl:1
	v_lshlrev_b32_e32 v48, 16, v32
	v_and_b32_e32 v49, 0xffff0000, v32
	v_add_f32_dpp v39, v39, v39 row_half_mirror row_mask:0xf bank_mask:0xf bound_ctrl:1
	v_mul_f32_e32 v54, 0x3c800000, v39
	v_pk_add_f32 v[42:43], v[42:43], v[54:55] op_sel_hi:[1,0] neg_lo:[0,1] neg_hi:[0,1]
	v_pk_add_f32 v[26:27], v[26:27], v[54:55] op_sel_hi:[1,0] neg_lo:[0,1] neg_hi:[0,1]
	v_pk_add_f32 v[44:45], v[44:45], v[54:55] op_sel_hi:[1,0] neg_lo:[0,1] neg_hi:[0,1]
	v_pk_add_f32 v[28:29], v[28:29], v[54:55] op_sel_hi:[1,0] neg_lo:[0,1] neg_hi:[0,1]
	v_pk_mul_f32 v[54:55], v[42:43], v[42:43]
	v_pk_mul_f32 v[56:57], v[26:27], v[26:27]
	v_add_f32_e32 v39, v54, v55
	v_add_f32_e32 v39, v56, v39
	v_pk_mul_f32 v[58:59], v[44:45], v[44:45]
	v_add_f32_e32 v39, v57, v39
	v_add_f32_e32 v39, v58, v39
	v_pk_mul_f32 v[60:61], v[28:29], v[28:29]
	v_add_f32_e32 v39, v59, v39
	v_add_f32_e32 v39, v60, v39
	v_add_f32_e32 v39, v61, v39
	v_lshlrev_b32_e32 v32, 16, v33
	v_and_b32_e32 v33, 0xffff0000, v33
	v_add_f32_dpp v39, v39, v39 quad_perm:[1,0,3,2] row_mask:0xf bank_mask:0xf bound_ctrl:1
	s_waitcnt vmcnt(5)
	v_lshlrev_b32_e32 v50, 16, v34
	v_and_b32_e32 v51, 0xffff0000, v34
	v_add_f32_dpp v39, v39, v39 quad_perm:[2,3,0,1] row_mask:0xf bank_mask:0xf bound_ctrl:1
	v_lshlrev_b32_e32 v34, 16, v35
	v_and_b32_e32 v35, 0xffff0000, v35
	v_add_f32_dpp v39, v39, v39 row_half_mirror row_mask:0xf bank_mask:0xf bound_ctrl:1
	v_fmamk_f32 v39, v39, 0x3c800000, v1
	v_mul_f32_e32 v54, 0x4b800000, v39
	v_cmp_gt_f32_e32 vcc, s13, v39
	v_lshlrev_b32_e32 v52, 16, v36
	v_and_b32_e32 v53, 0xffff0000, v36
	v_cndmask_b32_e32 v39, v39, v54, vcc
	v_rsq_f32_e32 v39, v39
	v_lshlrev_b32_e32 v36, 16, v37
	v_and_b32_e32 v37, 0xffff0000, v37
	v_mul_f32_e32 v54, 0x45800000, v39
	v_cndmask_b32_e32 v54, v39, v54, vcc
	v_pk_mul_f32 v[42:43], v[42:43], v[54:55] op_sel_hi:[1,0]
	v_pk_mul_f32 v[26:27], v[26:27], v[54:55] op_sel_hi:[1,0]
	v_pk_mul_f32 v[44:45], v[44:45], v[54:55] op_sel_hi:[1,0]
	v_pk_mul_f32 v[28:29], v[28:29], v[54:55] op_sel_hi:[1,0]
	v_pk_fma_f32 v[14:15], v[232:233], v[42:43], v[240:241]
	v_pk_fma_f32 v[16:17], v[234:235], v[26:27], v[242:243]
	v_pk_fma_f32 v[10:11], v[236:237], v[44:45], v[246:247]
	v_pk_fma_f32 v[12:13], v[238:239], v[28:29], v[248:249]
	s_waitcnt vmcnt(4)
	v_pk_fma_f32 v[14:15], v[38:39], v[46:47], v[14:15] op_sel_hi:[0,1,1]
	v_pk_fma_f32 v[16:17], v[38:39], v[30:31], v[16:17] op_sel_hi:[0,1,1]
	v_pk_fma_f32 v[10:11], v[38:39], v[48:49], v[10:11] op_sel_hi:[0,1,1]
	v_pk_fma_f32 v[12:13], v[38:39], v[32:33], v[12:13] op_sel_hi:[0,1,1]
	v_pk_mul_f32 v[14:15], v[14:15], v[50:51]
	v_pk_mul_f32 v[16:17], v[16:17], v[34:35]
	v_pk_mul_f32 v[18:19], v[10:11], v[52:53]
	v_pk_mul_f32 v[20:21], v[12:13], v[36:37]
	v_cvt_pk_bf16_f32 v10, v14, v15
	v_cvt_pk_bf16_f32 v11, v16, v17
	v_cvt_pk_bf16_f32 v12, v18, v19
	v_cvt_pk_bf16_f32 v13, v20, v21
	global_store_dwordx4 v[40:41], v[10:13], off
	s_waitcnt vmcnt(4)
	v_lshlrev_b32_e32 v106, 16, v90
	v_and_b32_e32 v107, 0xffff0000, v90
	v_add_f32_e32 v103, 0, v106
	v_lshlrev_b32_e32 v90, 16, v91
	v_add_f32_e32 v103, v103, v107
	v_and_b32_e32 v91, 0xffff0000, v91
	v_add_f32_e32 v103, v103, v90
	v_lshlrev_b32_e32 v108, 16, v92
	v_add_f32_e32 v103, v103, v91
	v_and_b32_e32 v109, 0xffff0000, v92
	v_add_f32_e32 v103, v103, v108
	v_lshlrev_b32_e32 v92, 16, v93
	v_add_f32_e32 v103, v103, v109
	v_and_b32_e32 v93, 0xffff0000, v93
	v_add_f32_e32 v103, v103, v92
	v_add_f32_e32 v103, v103, v93
	s_waitcnt vmcnt(3)
	v_lshlrev_b32_e32 v110, 16, v94
	v_and_b32_e32 v111, 0xffff0000, v94
	v_add_f32_dpp v103, v103, v103 quad_perm:[1,0,3,2] row_mask:0xf bank_mask:0xf bound_ctrl:1
	v_lshlrev_b32_e32 v94, 16, v95
	v_and_b32_e32 v95, 0xffff0000, v95
	v_add_f32_dpp v103, v103, v103 quad_perm:[2,3,0,1] row_mask:0xf bank_mask:0xf bound_ctrl:1
	v_lshlrev_b32_e32 v112, 16, v96
	v_and_b32_e32 v113, 0xffff0000, v96
	v_add_f32_dpp v103, v103, v103 row_half_mirror row_mask:0xf bank_mask:0xf bound_ctrl:1
	v_mul_f32_e32 v118, 0x3c800000, v103
	v_pk_add_f32 v[106:107], v[106:107], v[118:119] op_sel_hi:[1,0] neg_lo:[0,1] neg_hi:[0,1]
	v_pk_add_f32 v[90:91], v[90:91], v[118:119] op_sel_hi:[1,0] neg_lo:[0,1] neg_hi:[0,1]
	v_pk_add_f32 v[108:109], v[108:109], v[118:119] op_sel_hi:[1,0] neg_lo:[0,1] neg_hi:[0,1]
	v_pk_add_f32 v[92:93], v[92:93], v[118:119] op_sel_hi:[1,0] neg_lo:[0,1] neg_hi:[0,1]
	v_pk_mul_f32 v[118:119], v[106:107], v[106:107]
	v_pk_mul_f32 v[120:121], v[90:91], v[90:91]
	v_add_f32_e32 v103, v118, v119
	v_add_f32_e32 v103, v120, v103
	v_pk_mul_f32 v[122:123], v[108:109], v[108:109]
	v_add_f32_e32 v103, v121, v103
	v_add_f32_e32 v103, v122, v103
	v_pk_mul_f32 v[124:125], v[92:93], v[92:93]
	v_add_f32_e32 v103, v123, v103
	v_add_f32_e32 v103, v124, v103
	v_add_f32_e32 v103, v125, v103
	v_lshlrev_b32_e32 v96, 16, v97
	v_and_b32_e32 v97, 0xffff0000, v97
	v_add_f32_dpp v103, v103, v103 quad_perm:[1,0,3,2] row_mask:0xf bank_mask:0xf bound_ctrl:1
	s_waitcnt vmcnt(2)
	v_lshlrev_b32_e32 v114, 16, v98
	v_and_b32_e32 v115, 0xffff0000, v98
	v_add_f32_dpp v103, v103, v103 quad_perm:[2,3,0,1] row_mask:0xf bank_mask:0xf bound_ctrl:1
	v_lshlrev_b32_e32 v98, 16, v99
	v_and_b32_e32 v99, 0xffff0000, v99
	v_add_f32_dpp v103, v103, v103 row_half_mirror row_mask:0xf bank_mask:0xf bound_ctrl:1
	v_fmamk_f32 v103, v103, 0x3c800000, v1
	v_mul_f32_e32 v118, 0x4b800000, v103
	v_cmp_gt_f32_e32 vcc, s13, v103
	v_lshlrev_b32_e32 v116, 16, v100
	v_and_b32_e32 v117, 0xffff0000, v100
	v_cndmask_b32_e32 v103, v103, v118, vcc
	v_rsq_f32_e32 v103, v103
	v_lshlrev_b32_e32 v100, 16, v101
	v_and_b32_e32 v101, 0xffff0000, v101
	v_mul_f32_e32 v118, 0x45800000, v103
	v_cndmask_b32_e32 v118, v103, v118, vcc
	v_pk_mul_f32 v[106:107], v[106:107], v[118:119] op_sel_hi:[1,0]
	v_pk_mul_f32 v[90:91], v[90:91], v[118:119] op_sel_hi:[1,0]
	v_pk_mul_f32 v[108:109], v[108:109], v[118:119] op_sel_hi:[1,0]
	v_pk_mul_f32 v[92:93], v[92:93], v[118:119] op_sel_hi:[1,0]
	v_pk_fma_f32 v[78:79], v[232:233], v[106:107], v[240:241]
	v_pk_fma_f32 v[80:81], v[234:235], v[90:91], v[242:243]
	v_pk_fma_f32 v[74:75], v[236:237], v[108:109], v[246:247]
	v_pk_fma_f32 v[76:77], v[238:239], v[92:93], v[248:249]
	s_waitcnt vmcnt(1)
	v_pk_fma_f32 v[78:79], v[102:103], v[110:111], v[78:79] op_sel_hi:[0,1,1]
	v_pk_fma_f32 v[80:81], v[102:103], v[94:95], v[80:81] op_sel_hi:[0,1,1]
	v_pk_fma_f32 v[74:75], v[102:103], v[112:113], v[74:75] op_sel_hi:[0,1,1]
	v_pk_fma_f32 v[76:77], v[102:103], v[96:97], v[76:77] op_sel_hi:[0,1,1]
	v_pk_mul_f32 v[78:79], v[78:79], v[114:115]
	v_pk_mul_f32 v[80:81], v[80:81], v[98:99]
	v_pk_mul_f32 v[82:83], v[74:75], v[116:117]
	v_pk_mul_f32 v[84:85], v[76:77], v[100:101]
	v_cvt_pk_bf16_f32 v74, v78, v79
	v_cvt_pk_bf16_f32 v75, v80, v81
	v_cvt_pk_bf16_f32 v76, v82, v83
	v_cvt_pk_bf16_f32 v77, v84, v85
	global_store_dwordx4 v[104:105], v[74:77], off
	s_andn2_b64 exec, exec, s[10:11]
	s_cbranch_execnz .LBB0_1613
	s_branch .LBB0_1614
.Lp5_single:
	s_waitcnt vmcnt(6)
	v_ashrrev_i32_e32 v26, 1, v3
	v_ashrrev_i32_e32 v27, 31, v26
	v_lshlrev_b64 v[28:29], 11, v[26:27]
	v_lshlrev_b64 v[26:27], 6, v[26:27]
	v_lshl_or_b32 v28, v2, 1, v28
	s_waitcnt vmcnt(4)
	v_lshl_add_u64 v[38:39], v[4:5], 0, v[26:27]
	v_lshl_add_u64 v[40:41], s[4:5], 0, v[28:29]
	v_lshl_add_u64 v[30:31], s[6:7], 0, v[28:29]
	v_lshl_add_u64 v[34:35], s[8:9], 0, v[28:29]
	global_load_dwordx4 v[26:29], v[40:41], off
	s_nop 0
	global_load_dwordx4 v[30:33], v[30:31], off
	s_nop 0
	global_load_dwordx4 v[34:37], v[34:35], off
	s_nop 0
	global_load_dword v38, v[38:39], off
	v_add_u32_e32 v3, s12, v3
	v_cmp_lt_i32_e32 vcc, s14, v3
	s_or_b64 s[10:11], vcc, s[10:11]
	s_waitcnt vmcnt(3)
	v_lshlrev_b32_e32 v42, 16, v26
	v_and_b32_e32 v43, 0xffff0000, v26
	v_add_f32_e32 v39, 0, v42
	v_lshlrev_b32_e32 v26, 16, v27
	v_add_f32_e32 v39, v39, v43
	v_and_b32_e32 v27, 0xffff0000, v27
	v_add_f32_e32 v39, v39, v26
	v_lshlrev_b32_e32 v44, 16, v28
	v_add_f32_e32 v39, v39, v27
	v_and_b32_e32 v45, 0xffff0000, v28
	v_add_f32_e32 v39, v39, v44
	v_lshlrev_b32_e32 v28, 16, v29
	v_add_f32_e32 v39, v39, v45
	v_and_b32_e32 v29, 0xffff0000, v29
	v_add_f32_e32 v39, v39, v28
	v_add_f32_e32 v39, v39, v29
	s_waitcnt vmcnt(2)
	v_lshlrev_b32_e32 v46, 16, v30
	v_and_b32_e32 v47, 0xffff0000, v30
	v_add_f32_dpp v39, v39, v39 quad_perm:[1,0,3,2] row_mask:0xf bank_mask:0xf bound_ctrl:1
	v_lshlrev_b32_e32 v30, 16, v31
	v_and_b32_e32 v31, 0xffff0000, v31
	v_add_f32_dpp v39, v39, v39 quad_perm:[2,3,0,1] row_mask:0xf bank_mask:0xf bound_ctrl:1
	v_lshlrev_b32_e32 v48, 16, v32
	v_and_b32_e32 v49, 0xffff0000, v32
	v_add_f32_dpp v39, v39, v39 row_half_mirror row_mask:0xf bank_mask:0xf bound_ctrl:1
	v_mul_f32_e32 v54, 0x3c800000, v39
	v_pk_add_f32 v[42:43], v[42:43], v[54:55] op_sel_hi:[1,0] neg_lo:[0,1] neg_hi:[0,1]
	v_pk_add_f32 v[26:27], v[26:27], v[54:55] op_sel_hi:[1,0] neg_lo:[0,1] neg_hi:[0,1]
	v_pk_add_f32 v[44:45], v[44:45], v[54:55] op_sel_hi:[1,0] neg_lo:[0,1] neg_hi:[0,1]
	v_pk_add_f32 v[28:29], v[28:29], v[54:55] op_sel_hi:[1,0] neg_lo:[0,1] neg_hi:[0,1]
	v_pk_mul_f32 v[54:55], v[42:43], v[42:43]
	v_pk_mul_f32 v[56:57], v[26:27], v[26:27]
	v_add_f32_e32 v39, v54, v55
	v_add_f32_e32 v39, v56, v39
	v_pk_mul_f32 v[58:59], v[44:45], v[44:45]
	v_add_f32_e32 v39, v57, v39
	v_add_f32_e32 v39, v58, v39
	v_pk_mul_f32 v[60:61], v[28:29], v[28:29]
	v_add_f32_e32 v39, v59, v39
	v_add_f32_e32 v39, v60, v39
	v_add_f32_e32 v39, v61, v39
	v_lshlrev_b32_e32 v32, 16, v33
	v_and_b32_e32 v33, 0xffff0000, v33
	v_add_f32_dpp v39, v39, v39 quad_perm:[1,0,3,2] row_mask:0xf bank_mask:0xf bound_ctrl:1
	s_waitcnt vmcnt(1)
	v_lshlrev_b32_e32 v50, 16, v34
	v_and_b32_e32 v51, 0xffff0000, v34
	v_add_f32_dpp v39, v39, v39 quad_perm:[2,3,0,1] row_mask:0xf bank_mask:0xf bound_ctrl:1
	v_lshlrev_b32_e32 v34, 16, v35
	v_and_b32_e32 v35, 0xffff0000, v35
	v_add_f32_dpp v39, v39, v39 row_half_mirror row_mask:0xf bank_mask:0xf bound_ctrl:1
	v_fmamk_f32 v39, v39, 0x3c800000, v1
	v_mul_f32_e32 v54, 0x4b800000, v39
	v_cmp_gt_f32_e32 vcc, s13, v39
	v_lshlrev_b32_e32 v52, 16, v36
	v_and_b32_e32 v53, 0xffff0000, v36
	v_cndmask_b32_e32 v39, v39, v54, vcc
	v_rsq_f32_e32 v39, v39
	v_lshlrev_b32_e32 v36, 16, v37
	v_and_b32_e32 v37, 0xffff0000, v37
	v_mul_f32_e32 v54, 0x45800000, v39
	v_cndmask_b32_e32 v54, v39, v54, vcc
	v_pk_mul_f32 v[42:43], v[42:43], v[54:55] op_sel_hi:[1,0]
	v_pk_mul_f32 v[26:27], v[26:27], v[54:55] op_sel_hi:[1,0]
	v_pk_mul_f32 v[44:45], v[44:45], v[54:55] op_sel_hi:[1,0]
	v_pk_mul_f32 v[28:29], v[28:29], v[54:55] op_sel_hi:[1,0]
	v_pk_fma_f32 v[14:15], v[232:233], v[42:43], v[240:241]
	v_pk_fma_f32 v[16:17], v[234:235], v[26:27], v[242:243]
	v_pk_fma_f32 v[10:11], v[236:237], v[44:45], v[246:247]
	v_pk_fma_f32 v[12:13], v[238:239], v[28:29], v[248:249]
	s_waitcnt vmcnt(0)
	v_pk_fma_f32 v[14:15], v[38:39], v[46:47], v[14:15] op_sel_hi:[0,1,1]
	v_pk_fma_f32 v[16:17], v[38:39], v[30:31], v[16:17] op_sel_hi:[0,1,1]
	v_pk_fma_f32 v[10:11], v[38:39], v[48:49], v[10:11] op_sel_hi:[0,1,1]
	v_pk_fma_f32 v[12:13], v[38:39], v[32:33], v[12:13] op_sel_hi:[0,1,1]
	v_pk_mul_f32 v[14:15], v[14:15], v[50:51]
	v_pk_mul_f32 v[16:17], v[16:17], v[34:35]
	v_pk_mul_f32 v[18:19], v[10:11], v[52:53]
	v_pk_mul_f32 v[20:21], v[12:13], v[36:37]
	v_cvt_pk_bf16_f32 v10, v14, v15
	v_cvt_pk_bf16_f32 v11, v16, v17
	v_cvt_pk_bf16_f32 v12, v18, v19
	v_cvt_pk_bf16_f32 v13, v20, v21
	global_store_dwordx4 v[40:41], v[10:13], off
	s_andn2_b64 exec, exec, s[10:11]
	s_cbranch_execnz .LBB0_1613
